# a8 + B3 local (mla_prep tile remap to own-XCD row blocks) + B11 local: 8 of 12 grid barriers XCD-local
# speedup vs baseline: 1.0170x; 1.0043x over previous
.LBB0_512:
	s_or_b64 exec, exec, s[12:13]
	s_waitcnt vmcnt(0)
	s_waitcnt vmcnt(0)
.LBB0_513:
	s_andn2_saveexec_b64 s[6:7], s[6:7]
	s_cbranch_execz .LBB0_533
	s_mov_b64 s[6:7], exec
	v_mov_b32_e32 v1, 0x20008
	ds_read_b32 v1, v1
	s_waitcnt lgkmcnt(0)
	s_nop 0
	v_readfirstlane_b32 s32, v1
	s_nop 3
	s_cmp_eq_u32 s32, 0
	s_cbranch_scc1 .Lmy_fullbar_1
	v_mov_b32_e32 v1, 0x2000
	v_mov_b32_e32 v3, 1
	global_atomic_add v1, v3, s[4:5] offset:1024
	buffer_inv sc1
	s_waitcnt vmcnt(0)
	s_branch .LBB0_533
.Lmy_fullbar_1:
	buffer_wbl2 sc1
	buffer_inv sc1
	s_waitcnt lgkmcnt(0)
	s_waitcnt vmcnt(0)
	v_mbcnt_lo_u32_b32 v1, s6, 0
	v_mbcnt_hi_u32_b32 v1, s7, v1
	v_cmp_eq_u32_e32 vcc, 0, v1
	s_and_saveexec_b64 s[12:13], vcc
	s_cbranch_execz .LBB0_516
	s_bcnt1_i32_b64 s6, s[6:7]
	v_mov_b32_e32 v2, 0xfe03000
	v_mov_b32_e32 v3, s6
	global_atomic_add v2, v2, v3, s[26:27] offset:1024 sc0

.LBB0_533:
	s_or_b64 exec, exec, s[0:1]
	s_add_u32 s0, s26, 0x8e00000
	s_addc_u32 s1, s27, 0
	s_add_u32 s6, s26, 0xa600000
	s_addc_u32 s7, s27, 0
	s_add_u32 s12, s26, 0xbe00000
	s_waitcnt lgkmcnt(0)
	v_cndmask_b32_e64 v0, 0, 1, s[20:21]
	s_addc_u32 s13, s27, 0
	v_cmp_ne_u32_e64 s[4:5], 1, v0
	s_andn2_b64 vcc, exec, s[20:21]
	s_barrier
	v_mbcnt_lo_u32_b32 v0, -1, 0
	v_mbcnt_hi_u32_b32 v0, -1, v0
	s_cbranch_vccnz .LBB0_536
	s_and_b32 s62, s2, 7
	s_lshl_b32 s62, s62, 5
	s_lshr_b32 s63, s2, 3
	s_or_b32 s62, s62, s63
	s_cmp_eq_u32 s28, 0x100
	s_cselect_b32 s62, s62, s2
	s_add_u32 s20, s26, 0x5500000
	v_and_b32_e32 v218, 7, v0
	s_addc_u32 s21, s27, 0
	v_add_u32_e32 v1, s33, v0
	v_mul_u32_u24_e32 v0, 0x60, v218
	s_add_u32 s22, s26, 0x2600000
	v_lshlrev_b32_e32 v100, 1, v0
	v_mov_b32_e32 v101, 0
	s_addc_u32 s23, s27, 0
	v_lshl_add_u64 v[102:103], s[14:15], 0, v[100:101]
	v_lshlrev_b32_e32 v100, 8, v218
	s_add_u32 s38, s26, 0x2700000
	v_ashrrev_i32_e32 v2, 3, v1
	v_lshl_add_u64 v[104:105], s[18:19], 0, v[100:101]
	v_lshlrev_b32_e32 v100, 5, v218
	v_lshlrev_b32_e32 v0, 6, v218
	v_mov_b32_e32 v1, v101
	s_mov_b32 s14, 0x3c2aaaab
	s_addc_u32 s39, s27, 0
	v_lshl_add_u64 v[106:107], s[10:11], 0, v[0:1]
	v_lshl_add_u64 v[108:109], s[16:17], 0, v[100:101]
	v_lshl_add_u32 v110, s62, 6, v2
	s_lshl_b32 s16, s28, 6
	s_movk_i32 s17, 0x1fff
	s_movk_i32 s18, 0x600
	v_mov_b32_e32 v100, 0x358637bd
	s_mov_b32 s19, 0x800000
	s_movk_i32 s35, 0xc0
	v_mov_b64_e32 v[112:113], s[0:1]
	s_brev_b32 s15, 60
	v_mov_b64_e32 v[114:115], s[6:7]
	s_mov_b32 s40, s62

.LBB0_1205:
	s_andn2_saveexec_b64 s[8:9], s[16:17]
	s_cbranch_execz .LBB0_1225
	s_mov_b64 s[16:17], exec
	v_mov_b32_e32 v1, 0x20008
	ds_read_b32 v1, v1
	s_waitcnt lgkmcnt(0)
	s_nop 0
	v_readfirstlane_b32 s32, v1
	s_nop 3
	s_cmp_eq_u32 s32, 0
	s_cbranch_scc1 .Lmy_fullbar_6
	v_mov_b32_e32 v1, 0x2000
	v_mov_b32_e32 v3, 1
	global_atomic_add v1, v3, s[6:7] offset:1024
	buffer_inv sc1
	s_waitcnt vmcnt(0)
	s_branch .LBB0_1225
.Lmy_fullbar_6:
	buffer_wbl2 sc1
	buffer_inv sc1
	s_waitcnt lgkmcnt(0)
	s_waitcnt vmcnt(0)
	v_mbcnt_lo_u32_b32 v1, s16, 0
	v_mbcnt_hi_u32_b32 v1, s17, v1
	v_cmp_eq_u32_e32 vcc, 0, v1
	s_and_saveexec_b64 s[18:19], vcc
	s_cbranch_execz .LBB0_1208
	s_bcnt1_i32_b64 s3, s[16:17]
	v_mov_b32_e32 v2, 0xfe03000
	v_mov_b32_e32 v3, s3
	global_atomic_add v2, v2, v3, s[26:27] offset:1024 sc0
